# gate and T loads of the merged-pass epilogues issued ahead (all up front in pass A, one batch ahead in pass B)
# baseline (speedup 1.0000x reference)
.LBB0_1342:
	s_lshl_b32 s13, s73, 8
	v_mov_b32_e32 v130, v195
	v_mov_b32_e32 v131, v210
	s_add_i32 s13, s13, s61
	v_add_u32_e32 v134, s13, v130
	s_lshl_b32 s13, s6, 8
	s_or_b32 s13, s13, s62
	v_lshl_add_u32 v130, v131, 3, s13
	v_bfe_u32 v133, v130, 5, 1
	v_lshrrev_b32_e32 v137, 3, v134
	v_and_or_b32 v137, v137, 14, v133
	v_lshlrev_b32_e32 v131, 1, v130
	v_lshlrev_b32_e32 v138, 6, v134
	v_lshlrev_b32_e32 v166, 10, v137
	v_lshlrev_b32_e32 v137, 2, v134
	v_and_b32_e32 v132, 48, v131
	v_ashrrev_i32_e32 v135, 3, v134
	v_lshlrev_b32_e32 v136, 7, v134
	v_and_b32_e32 v138, 0x3c0, v138
	v_and_b32_e32 v137, 32, v137
	v_ashrrev_i32_e32 v131, 6, v130
	v_and_b32_e32 v135, 0xffffffe0, v135
	v_and_b32_e32 v136, 0x4000, v136
	v_bitop3_b32 v137, v132, v137, v138 bitop3:0x36
	v_or3_b32 v198, v136, v137, v166
	v_add_u32_e32 v136, v131, v135
	v_ashrrev_i32_e32 v137, 31, v136
	v_add_u32_e32 v130, 0x80, v130
	v_lshl_add_u64 v[140:141], s[2:3], 0, v[198:199]
	v_lshlrev_b64 v[136:137], 15, v[136:137]
	v_ashrrev_i32_e32 v130, 6, v130
	v_lshl_add_u64 v[136:137], v[140:141], 0, v[136:137]
	v_lshl_add_u64 v[168:169], v[136:137], 0, 0
	global_load_dwordx4 v[136:139], v[136:137], off
	s_mov_b32 s98, 0x11000
	s_mov_b32 s99, 0x0
	v_lshl_add_u64 v[170:171], v[168:169], 0, s[98:99]
	global_load_dwordx4 v[140:143], v[170:171], off offset:-4096
	s_mov_b32 s98, 0x1000
	s_mov_b32 s99, 0x0
	v_lshl_add_u64 v[172:173], v[168:169], 0, s[98:99]
	global_load_dwordx4 v[144:147], v[172:173], off offset:-2048
	global_load_dwordx4 v[148:151], v[170:171], off offset:-2048
	s_mov_b32 s98, 0x5000
	s_mov_b32 s99, 0x0
	v_lshl_add_u64 v[192:193], v[168:169], 0, s[98:99]
	s_mov_b32 s98, 0x15000
	s_mov_b32 s99, 0x0
	v_lshl_add_u64 v[254:255], v[168:169], 0, s[98:99]
	global_load_dwordx4 v[180:183], v[172:173], off
	global_load_dwordx4 v[184:187], v[170:171], off
	global_load_dwordx4 v[188:191], v[172:173], off offset:2048
	global_load_dwordx4 v[212:215], v[170:171], off offset:2048
	global_load_dwordx4 v[216:219], v[192:193], off offset:-4096
	global_load_dwordx4 v[220:223], v[254:255], off offset:-4096
	global_load_dwordx4 v[224:227], v[192:193], off offset:-2048
	global_load_dwordx4 v[228:231], v[254:255], off offset:-2048
	global_load_dwordx4 v[232:235], v[192:193], off
	global_load_dwordx4 v[236:239], v[254:255], off
	global_load_dwordx4 v[240:243], v[192:193], off offset:2048
	global_load_dwordx4 v[250:253], v[254:255], off offset:2048
	v_ashrrev_i32_e32 v154, 4, v134
	v_and_b32_e32 v167, -16, v154
	v_add_u32_e32 v154, v131, v167
	v_ashrrev_i32_e32 v155, 31, v154
	v_lshlrev_b64 v[154:155], 15, v[154:155]
	v_lshl_add_u64 v[154:155], s[10:11], 0, v[154:155]
	v_lshl_add_u64 v[154:155], v[154:155], 0, v[198:199]
	s_andn2_b64 vcc, exec, s[38:39]
	s_waitcnt vmcnt(15)
	v_lshlrev_b32_e32 v156, 16, v136
	v_and_b32_e32 v157, 0xffff0000, v136
	v_lshlrev_b32_e32 v136, 16, v137
	v_and_b32_e32 v137, 0xffff0000, v137
	v_lshlrev_b32_e32 v158, 16, v138
	v_and_b32_e32 v159, 0xffff0000, v138
	v_lshlrev_b32_e32 v138, 16, v139
	v_and_b32_e32 v139, 0xffff0000, v139
	v_pk_mul_f32 v[156:157], v[126:127], v[156:157]
	v_pk_mul_f32 v[162:163], v[128:129], v[136:137]
	v_pk_mul_f32 v[158:159], v[122:123], v[158:159]
	v_pk_mul_f32 v[164:165], v[124:125], v[138:139]
	v_cvt_pk_bf16_f32 v136, v156, v157
	v_cvt_pk_bf16_f32 v137, v162, v163
	v_cvt_pk_bf16_f32 v138, v158, v159
	v_cvt_pk_bf16_f32 v139, v164, v165
	s_waitcnt vmcnt(14)
	v_lshlrev_b32_e32 v160, 16, v140
	v_and_b32_e32 v161, 0xffff0000, v140
	v_lshlrev_b32_e32 v140, 16, v141
	v_lshl_add_u64 v[174:175], v[154:155], 0, 0
	global_store_dwordx4 v[154:155], v[136:139], off
	v_and_b32_e32 v141, 0xffff0000, v141
	v_pk_mul_f32 v[160:161], v[94:95], v[160:161]
	v_lshlrev_b32_e32 v136, 16, v142
	v_and_b32_e32 v137, 0xffff0000, v142
	v_pk_mul_f32 v[138:139], v[96:97], v[140:141]
	v_pk_mul_f32 v[140:141], v[90:91], v[136:137]
	v_lshlrev_b32_e32 v136, 16, v143
	v_and_b32_e32 v137, 0xffff0000, v143
	v_pk_mul_f32 v[142:143], v[92:93], v[136:137]
	v_cvt_pk_bf16_f32 v136, v160, v161
	v_cvt_pk_bf16_f32 v137, v138, v139
	v_cvt_pk_bf16_f32 v138, v140, v141
	v_cvt_pk_bf16_f32 v139, v142, v143
	s_mov_b32 s98, 0x11000
	s_mov_b32 s99, 0x0
	v_lshl_add_u64 v[176:177], v[174:175], 0, s[98:99]
	global_store_dwordx4 v[176:177], v[136:139], off offset:-4096
	s_waitcnt vmcnt(15)
	v_lshlrev_b32_e32 v140, 16, v146
	v_and_b32_e32 v141, 0xffff0000, v146
	v_lshlrev_b32_e32 v136, 16, v144
	v_and_b32_e32 v137, 0xffff0000, v144
	v_lshlrev_b32_e32 v138, 16, v145
	v_and_b32_e32 v139, 0xffff0000, v145
	v_lshlrev_b32_e32 v142, 16, v147
	v_and_b32_e32 v143, 0xffff0000, v147
	v_pk_mul_f32 v[136:137], v[118:119], v[136:137]
	v_pk_mul_f32 v[138:139], v[120:121], v[138:139]
	v_pk_mul_f32 v[140:141], v[114:115], v[140:141]
	v_pk_mul_f32 v[142:143], v[116:117], v[142:143]
	v_cvt_pk_bf16_f32 v136, v136, v137
	v_cvt_pk_bf16_f32 v137, v138, v139
	v_cvt_pk_bf16_f32 v138, v140, v141
	v_cvt_pk_bf16_f32 v139, v142, v143
	s_mov_b32 s98, 0x1000
	s_mov_b32 s99, 0x0
	v_lshl_add_u64 v[178:179], v[174:175], 0, s[98:99]
	global_store_dwordx4 v[178:179], v[136:139], off offset:-2048
	s_nop 0
	s_nop 0
	s_waitcnt vmcnt(15)
	v_lshlrev_b32_e32 v136, 16, v148
	v_and_b32_e32 v137, 0xffff0000, v148
	v_lshlrev_b32_e32 v138, 16, v149
	v_and_b32_e32 v139, 0xffff0000, v149
	v_lshlrev_b32_e32 v140, 16, v150
	v_and_b32_e32 v141, 0xffff0000, v150
	v_lshlrev_b32_e32 v142, 16, v151
	v_and_b32_e32 v143, 0xffff0000, v151
	v_pk_mul_f32 v[136:137], v[86:87], v[136:137]
	v_pk_mul_f32 v[138:139], v[88:89], v[138:139]
	v_pk_mul_f32 v[140:141], v[82:83], v[140:141]
	v_pk_mul_f32 v[142:143], v[84:85], v[142:143]
	v_cvt_pk_bf16_f32 v136, v136, v137
	v_cvt_pk_bf16_f32 v137, v138, v139
	v_cvt_pk_bf16_f32 v138, v140, v141
	v_cvt_pk_bf16_f32 v139, v142, v143
	global_store_dwordx4 v[176:177], v[136:139], off offset:-2048
	s_nop 0
	s_nop 0
	s_nop 0
	s_nop 0
	s_nop 0
	s_waitcnt vmcnt(12)
	v_mov_b32_e32 v136, v180
	v_mov_b32_e32 v137, v181
	v_mov_b32_e32 v138, v182
	v_mov_b32_e32 v139, v183
	v_mov_b32_e32 v140, v184
	v_mov_b32_e32 v141, v185
	v_mov_b32_e32 v142, v186
	v_mov_b32_e32 v143, v187
	v_mov_b32_e32 v144, v188
	v_mov_b32_e32 v145, v189
	v_mov_b32_e32 v146, v190
	v_mov_b32_e32 v147, v191
	v_mov_b32_e32 v148, v212
	v_mov_b32_e32 v149, v213
	v_mov_b32_e32 v150, v214
	v_mov_b32_e32 v151, v215
	v_lshlrev_b32_e32 v154, 16, v136
	v_and_b32_e32 v155, 0xffff0000, v136
	v_lshlrev_b32_e32 v136, 16, v137
	v_and_b32_e32 v137, 0xffff0000, v137
	v_pk_mul_f32 v[156:157], v[112:113], v[136:137]
	v_lshlrev_b32_e32 v136, 16, v138
	v_and_b32_e32 v137, 0xffff0000, v138
	v_pk_mul_f32 v[158:159], v[106:107], v[136:137]
	v_lshlrev_b32_e32 v136, 16, v139
	v_and_b32_e32 v137, 0xffff0000, v139
	v_pk_mul_f32 v[160:161], v[108:109], v[136:137]
	v_pk_mul_f32 v[154:155], v[110:111], v[154:155]
	v_cvt_pk_bf16_f32 v136, v154, v155
	v_cvt_pk_bf16_f32 v137, v156, v157
	v_cvt_pk_bf16_f32 v138, v158, v159
	v_cvt_pk_bf16_f32 v139, v160, v161
	global_store_dwordx4 v[178:179], v[136:139], off
	s_nop 0
	s_nop 0
	v_lshlrev_b32_e32 v136, 16, v140
	v_and_b32_e32 v137, 0xffff0000, v140
	v_lshlrev_b32_e32 v138, 16, v141
	v_and_b32_e32 v139, 0xffff0000, v141
	v_lshlrev_b32_e32 v140, 16, v142
	v_and_b32_e32 v141, 0xffff0000, v142
	v_lshlrev_b32_e32 v142, 16, v143
	v_and_b32_e32 v143, 0xffff0000, v143
	v_pk_mul_f32 v[136:137], v[78:79], v[136:137]
	v_pk_mul_f32 v[138:139], v[80:81], v[138:139]
	v_pk_mul_f32 v[140:141], v[74:75], v[140:141]
	v_pk_mul_f32 v[142:143], v[76:77], v[142:143]
	v_cvt_pk_bf16_f32 v136, v136, v137
	v_cvt_pk_bf16_f32 v137, v138, v139
	v_cvt_pk_bf16_f32 v138, v140, v141
	v_cvt_pk_bf16_f32 v139, v142, v143
	global_store_dwordx4 v[176:177], v[136:139], off
	v_lshlrev_b32_e32 v140, 16, v146
	v_and_b32_e32 v141, 0xffff0000, v146
	v_lshlrev_b32_e32 v136, 16, v144
	v_and_b32_e32 v137, 0xffff0000, v144
	v_lshlrev_b32_e32 v138, 16, v145
	v_and_b32_e32 v139, 0xffff0000, v145
	v_lshlrev_b32_e32 v142, 16, v147
	v_and_b32_e32 v143, 0xffff0000, v147
	v_pk_mul_f32 v[136:137], v[102:103], v[136:137]
	v_pk_mul_f32 v[138:139], v[104:105], v[138:139]
	v_pk_mul_f32 v[140:141], v[98:99], v[140:141]
	v_pk_mul_f32 v[142:143], v[100:101], v[142:143]
	v_cvt_pk_bf16_f32 v136, v136, v137
	v_cvt_pk_bf16_f32 v137, v138, v139
	v_cvt_pk_bf16_f32 v138, v140, v141
	v_cvt_pk_bf16_f32 v139, v142, v143
	global_store_dwordx4 v[178:179], v[136:139], off offset:2048
	s_nop 0
	s_nop 0
	v_lshlrev_b32_e32 v136, 16, v148
	v_and_b32_e32 v137, 0xffff0000, v148
	v_lshlrev_b32_e32 v138, 16, v149
	v_and_b32_e32 v139, 0xffff0000, v149
	v_lshlrev_b32_e32 v140, 16, v150
	v_and_b32_e32 v141, 0xffff0000, v150
	v_lshlrev_b32_e32 v142, 16, v151
	v_and_b32_e32 v143, 0xffff0000, v151
	v_pk_mul_f32 v[136:137], v[70:71], v[136:137]
	v_pk_mul_f32 v[138:139], v[72:73], v[138:139]
	v_pk_mul_f32 v[140:141], v[66:67], v[140:141]
	v_pk_mul_f32 v[142:143], v[68:69], v[142:143]
	v_cvt_pk_bf16_f32 v136, v136, v137
	v_cvt_pk_bf16_f32 v137, v138, v139
	v_cvt_pk_bf16_f32 v138, v140, v141
	v_cvt_pk_bf16_f32 v139, v142, v143
	v_add_u32_e32 v135, 0x80, v134
	global_store_dwordx4 v[176:177], v[136:139], off offset:2048
	v_add_u32_e32 v164, 0x90, v134
	s_nop 0
	s_nop 0
	v_lshlrev_b32_e32 v137, 6, v135
	v_lshlrev_b32_e32 v138, 2, v135
	v_lshlrev_b32_e32 v136, 7, v135
	v_and_b32_e32 v137, 0x3c0, v137
	v_and_b32_e32 v138, 32, v138
	v_and_b32_e32 v136, 0x4000, v136
	v_bitop3_b32 v137, v137, v138, v132 bitop3:0x36
	v_or3_b32 v198, v136, v137, v166
	s_mov_b32 s98, 0x5000
	s_mov_b32 s99, 0x0
	v_lshl_add_u64 v[170:171], v[168:169], 0, s[98:99]
	s_waitcnt vmcnt(12)
	v_mov_b32_e32 v136, v216
	v_mov_b32_e32 v137, v217
	v_mov_b32_e32 v138, v218
	v_mov_b32_e32 v139, v219
	s_mov_b32 s98, 0x15000
	s_mov_b32 s99, 0x0
	v_lshl_add_u64 v[172:173], v[168:169], 0, s[98:99]
	v_mov_b32_e32 v140, v220
	v_mov_b32_e32 v141, v221
	v_mov_b32_e32 v142, v222
	v_mov_b32_e32 v143, v223
	v_mov_b32_e32 v144, v224
	v_mov_b32_e32 v145, v225
	v_mov_b32_e32 v146, v226
	v_mov_b32_e32 v147, v227
	v_mov_b32_e32 v148, v228
	v_mov_b32_e32 v149, v229
	v_mov_b32_e32 v150, v230
	v_mov_b32_e32 v151, v231
	v_ashrrev_i32_e32 v135, 4, v135
	v_and_b32_e32 v135, -16, v135
	v_lshlrev_b32_e32 v154, 16, v136
	v_and_b32_e32 v155, 0xffff0000, v136
	v_lshlrev_b32_e32 v136, 16, v137
	v_and_b32_e32 v137, 0xffff0000, v137
	v_pk_mul_f32 v[156:157], v[64:65], v[136:137]
	v_lshlrev_b32_e32 v136, 16, v138
	v_and_b32_e32 v137, 0xffff0000, v138
	v_pk_mul_f32 v[158:159], v[58:59], v[136:137]
	v_lshlrev_b32_e32 v136, 16, v139
	v_and_b32_e32 v137, 0xffff0000, v139
	v_pk_mul_f32 v[160:161], v[60:61], v[136:137]
	v_add_u32_e32 v136, v135, v131
	v_ashrrev_i32_e32 v137, 31, v136
	v_lshlrev_b64 v[136:137], 15, v[136:137]
	v_pk_mul_f32 v[154:155], v[62:63], v[154:155]
	v_lshl_add_u64 v[136:137], s[10:11], 0, v[136:137]
	v_lshl_add_u64 v[162:163], v[136:137], 0, v[198:199]
	v_cvt_pk_bf16_f32 v136, v154, v155
	v_cvt_pk_bf16_f32 v137, v156, v157
	v_cvt_pk_bf16_f32 v138, v158, v159
	v_cvt_pk_bf16_f32 v139, v160, v161
	s_mov_b32 s98, 0x5000
	s_mov_b32 s99, 0x0
	v_lshl_add_u64 v[168:169], v[174:175], 0, s[98:99]
	global_store_dwordx4 v[168:169], v[136:139], off offset:-4096
	s_nop 0
	s_nop 0
	v_lshlrev_b32_e32 v136, 16, v140
	v_and_b32_e32 v137, 0xffff0000, v140
	v_lshlrev_b32_e32 v138, 16, v141
	v_and_b32_e32 v139, 0xffff0000, v141
	v_lshlrev_b32_e32 v140, 16, v142
	v_and_b32_e32 v141, 0xffff0000, v142
	v_lshlrev_b32_e32 v142, 16, v143
	v_and_b32_e32 v143, 0xffff0000, v143
	v_pk_mul_f32 v[136:137], v[30:31], v[136:137]
	v_pk_mul_f32 v[138:139], v[32:33], v[138:139]
	v_pk_mul_f32 v[140:141], v[26:27], v[140:141]
	v_pk_mul_f32 v[142:143], v[28:29], v[142:143]
	v_cvt_pk_bf16_f32 v136, v136, v137
	v_cvt_pk_bf16_f32 v137, v138, v139
	v_cvt_pk_bf16_f32 v138, v140, v141
	v_cvt_pk_bf16_f32 v139, v142, v143
	s_mov_b32 s98, 0x15000
	s_mov_b32 s99, 0x0
	v_lshl_add_u64 v[176:177], v[174:175], 0, s[98:99]
	global_store_dwordx4 v[176:177], v[136:139], off offset:-4096
	v_lshlrev_b32_e32 v140, 16, v146
	v_and_b32_e32 v141, 0xffff0000, v146
	v_lshlrev_b32_e32 v136, 16, v144
	v_and_b32_e32 v137, 0xffff0000, v144
	v_lshlrev_b32_e32 v138, 16, v145
	v_and_b32_e32 v139, 0xffff0000, v145
	v_lshlrev_b32_e32 v142, 16, v147
	v_and_b32_e32 v143, 0xffff0000, v147
	v_pk_mul_f32 v[136:137], v[54:55], v[136:137]
	v_pk_mul_f32 v[138:139], v[56:57], v[138:139]
	v_pk_mul_f32 v[140:141], v[50:51], v[140:141]
	v_pk_mul_f32 v[142:143], v[52:53], v[142:143]
	v_cvt_pk_bf16_f32 v136, v136, v137
	v_cvt_pk_bf16_f32 v137, v138, v139
	v_cvt_pk_bf16_f32 v138, v140, v141
	v_cvt_pk_bf16_f32 v139, v142, v143
	global_store_dwordx4 v[168:169], v[136:139], off offset:-2048
	s_nop 0
	s_nop 0
	v_lshlrev_b32_e32 v136, 16, v148
	v_and_b32_e32 v137, 0xffff0000, v148
	v_lshlrev_b32_e32 v138, 16, v149
	v_and_b32_e32 v139, 0xffff0000, v149
	v_lshlrev_b32_e32 v140, 16, v150
	v_and_b32_e32 v141, 0xffff0000, v150
	v_lshlrev_b32_e32 v142, 16, v151
	v_and_b32_e32 v143, 0xffff0000, v151
	v_pk_mul_f32 v[136:137], v[22:23], v[136:137]
	v_pk_mul_f32 v[138:139], v[24:25], v[138:139]
	v_pk_mul_f32 v[140:141], v[18:19], v[140:141]
	v_pk_mul_f32 v[142:143], v[20:21], v[142:143]
	v_cvt_pk_bf16_f32 v136, v136, v137
	v_cvt_pk_bf16_f32 v137, v138, v139
	v_cvt_pk_bf16_f32 v138, v140, v141
	v_cvt_pk_bf16_f32 v139, v142, v143
	v_add_u32_e32 v150, 0xa0, v134
	global_store_dwordx4 v[176:177], v[136:139], off offset:-2048
	s_nop 0
	s_nop 0
	v_lshrrev_b32_e32 v137, 3, v150
	v_lshlrev_b32_e32 v138, 6, v150
	v_lshlrev_b32_e32 v139, 2, v150
	v_lshlrev_b32_e32 v136, 7, v150
	v_and_or_b32 v137, v137, 14, v133
	v_and_b32_e32 v138, 0x3c0, v138
	v_and_b32_e32 v139, 32, v139
	v_and_b32_e32 v136, 0x4000, v136
	v_lshlrev_b32_e32 v137, 10, v137
	v_bitop3_b32 v138, v138, v139, v132 bitop3:0x36
	v_or3_b32 v198, v137, v136, v138
	s_waitcnt vmcnt(12)
	v_mov_b32_e32 v136, v232
	v_mov_b32_e32 v137, v233
	v_mov_b32_e32 v138, v234
	v_mov_b32_e32 v139, v235
	v_add_u32_e32 v160, 0xb0, v134
	v_lshrrev_b32_e32 v135, 3, v160
	v_and_or_b32 v133, v135, 14, v133
	v_lshlrev_b32_e32 v135, 6, v160
	v_lshlrev_b32_e32 v144, 2, v160
	v_lshlrev_b32_e32 v134, 7, v160
	v_and_b32_e32 v135, 0x3c0, v135
	v_and_b32_e32 v144, 32, v144
	v_and_b32_e32 v134, 0x4000, v134
	v_lshlrev_b32_e32 v133, 10, v133
	v_bitop3_b32 v132, v135, v144, v132 bitop3:0x36
	v_mov_b32_e32 v140, v236
	v_mov_b32_e32 v141, v237
	v_mov_b32_e32 v142, v238
	v_mov_b32_e32 v143, v239
	v_or3_b32 v148, v133, v134, v132
	v_mov_b32_e32 v149, v199
	v_mov_b32_e32 v132, v240
	v_mov_b32_e32 v133, v241
	v_mov_b32_e32 v134, v242
	v_mov_b32_e32 v135, v243
	v_mov_b32_e32 v144, v250
	v_mov_b32_e32 v145, v251
	v_mov_b32_e32 v146, v252
	v_mov_b32_e32 v147, v253
	v_ashrrev_i32_e32 v150, 4, v150
	v_and_b32_e32 v161, -16, v150
	v_lshlrev_b32_e32 v150, 16, v136
	v_and_b32_e32 v151, 0xffff0000, v136
	v_lshlrev_b32_e32 v136, 16, v137
	v_and_b32_e32 v137, 0xffff0000, v137
	v_pk_mul_f32 v[152:153], v[48:49], v[136:137]
	v_lshlrev_b32_e32 v136, 16, v138
	v_and_b32_e32 v137, 0xffff0000, v138
	v_pk_mul_f32 v[154:155], v[42:43], v[136:137]
	v_lshlrev_b32_e32 v136, 16, v139
	v_and_b32_e32 v137, 0xffff0000, v139
	v_pk_mul_f32 v[156:157], v[44:45], v[136:137]
	v_add_u32_e32 v136, v161, v131
	v_ashrrev_i32_e32 v137, 31, v136
	v_lshlrev_b64 v[136:137], 15, v[136:137]
	v_pk_mul_f32 v[150:151], v[46:47], v[150:151]
	v_lshl_add_u64 v[136:137], s[10:11], 0, v[136:137]
	v_lshl_add_u64 v[158:159], v[136:137], 0, v[198:199]
	v_cvt_pk_bf16_f32 v136, v150, v151
	v_cvt_pk_bf16_f32 v137, v152, v153
	v_cvt_pk_bf16_f32 v138, v154, v155
	v_cvt_pk_bf16_f32 v139, v156, v157
	global_store_dwordx4 v[168:169], v[136:139], off
	s_nop 0
	s_nop 0
	v_lshlrev_b32_e32 v136, 16, v140
	v_and_b32_e32 v137, 0xffff0000, v140
	v_lshlrev_b32_e32 v138, 16, v141
	v_and_b32_e32 v139, 0xffff0000, v141
	v_lshlrev_b32_e32 v140, 16, v142
	v_and_b32_e32 v141, 0xffff0000, v142
	v_lshlrev_b32_e32 v142, 16, v143
	v_and_b32_e32 v143, 0xffff0000, v143
	v_pk_mul_f32 v[136:137], v[14:15], v[136:137]
	v_pk_mul_f32 v[138:139], v[16:17], v[138:139]
	v_pk_mul_f32 v[140:141], v[10:11], v[140:141]
	v_pk_mul_f32 v[142:143], v[12:13], v[142:143]
	v_cvt_pk_bf16_f32 v136, v136, v137
	v_cvt_pk_bf16_f32 v137, v138, v139
	v_cvt_pk_bf16_f32 v138, v140, v141
	v_cvt_pk_bf16_f32 v139, v142, v143
	global_store_dwordx4 v[176:177], v[136:139], off
	s_nop 1
	v_ashrrev_i32_e32 v136, 4, v160
	v_and_b32_e32 v152, -16, v136
	v_lshlrev_b32_e32 v136, 16, v132
	v_and_b32_e32 v137, 0xffff0000, v132
	v_lshlrev_b32_e32 v132, 16, v133
	v_and_b32_e32 v133, 0xffff0000, v133
	v_pk_mul_f32 v[138:139], v[40:41], v[132:133]
	v_lshlrev_b32_e32 v132, 16, v134
	v_and_b32_e32 v133, 0xffff0000, v134
	v_pk_mul_f32 v[140:141], v[34:35], v[132:133]
	v_lshlrev_b32_e32 v132, 16, v135
	v_and_b32_e32 v133, 0xffff0000, v135
	v_pk_mul_f32 v[142:143], v[36:37], v[132:133]
	v_add_u32_e32 v132, v152, v131
	v_ashrrev_i32_e32 v133, 31, v132
	v_lshlrev_b64 v[132:133], 15, v[132:133]
	v_pk_mul_f32 v[136:137], v[38:39], v[136:137]
	v_lshl_add_u64 v[132:133], s[10:11], 0, v[132:133]
	v_add_u32_e32 v130, v130, v152
	v_lshl_add_u64 v[150:151], v[132:133], 0, v[148:149]
	v_cvt_pk_bf16_f32 v132, v136, v137
	v_cvt_pk_bf16_f32 v133, v138, v139
	v_cvt_pk_bf16_f32 v134, v140, v141
	v_cvt_pk_bf16_f32 v135, v142, v143
	v_ashrrev_i32_e32 v131, 31, v130
	global_store_dwordx4 v[168:169], v[132:135], off offset:2048
	v_lshlrev_b32_e32 v136, 16, v146
	v_and_b32_e32 v137, 0xffff0000, v146
	v_lshlrev_b32_e32 v132, 16, v144
	v_and_b32_e32 v133, 0xffff0000, v144
	v_lshlrev_b32_e32 v134, 16, v145
	v_and_b32_e32 v135, 0xffff0000, v145
	v_lshlrev_b32_e32 v138, 16, v147
	v_and_b32_e32 v139, 0xffff0000, v147
	v_lshlrev_b64 v[130:131], 15, v[130:131]
	v_pk_mul_f32 v[132:133], v[6:7], v[132:133]
	v_pk_mul_f32 v[134:135], v[8:9], v[134:135]
	v_pk_mul_f32 v[136:137], v[2:3], v[136:137]
	v_pk_mul_f32 v[138:139], v[4:5], v[138:139]
	v_lshl_add_u64 v[130:131], s[10:11], 0, v[130:131]
	v_lshl_add_u64 v[140:141], v[130:131], 0, v[148:149]
	v_cvt_pk_bf16_f32 v130, v132, v133
	v_cvt_pk_bf16_f32 v131, v134, v135
	v_cvt_pk_bf16_f32 v132, v136, v137
	v_cvt_pk_bf16_f32 v133, v138, v139
	global_store_dwordx4 v[176:177], v[130:133], off offset:2048
	s_cbranch_vccnz .LBB0_1303
	s_andn2_b64 vcc, exec, s[18:19]
	s_cbranch_vccnz .LBB0_1302
	s_barrier
	s_branch .LBB0_1302

.LBB0_1378:
	s_lshl_b32 s6, s69, 8
	v_mov_b32_e32 v130, v210
	v_mov_b32_e32 v131, v195
	s_add_i32 s6, s6, s57
	v_add_u32_e32 v177, s6, v131
	s_lshl_b32 s6, s12, 8
	s_or_b32 s6, s6, s58
	v_lshl_add_u32 v138, v130, 3, s6
	v_bfe_u32 v176, v138, 5, 1
	v_lshrrev_b32_e32 v131, 3, v177
	v_lshlrev_b32_e32 v130, 1, v138
	v_and_or_b32 v131, v131, 14, v176
	v_and_b32_e32 v175, 48, v130
	v_add_u32_e32 v130, 0x400, v138
	v_lshlrev_b32_e32 v132, 6, v177
	v_lshlrev_b32_e32 v181, 10, v131
	v_lshlrev_b32_e32 v131, 2, v177
	v_ashrrev_i32_e32 v174, 6, v130
	v_ashrrev_i32_e32 v130, 3, v177
	v_and_b32_e32 v132, 0x3c0, v132
	v_and_b32_e32 v131, 32, v131
	v_and_b32_e32 v139, 0xffffffe0, v130
	v_lshlrev_b32_e32 v130, 7, v177
	v_bitop3_b32 v131, v175, v131, v132 bitop3:0x36
	v_ashrrev_i32_e32 v132, 4, v177
	v_and_b32_e32 v130, 0x4000, v130
	v_and_b32_e32 v140, -16, v132
	v_add_u32_e32 v134, v174, v139
	v_ashrrev_i32_e32 v178, 6, v138
	v_or3_b32 v154, v130, v131, v181
	v_ashrrev_i32_e32 v135, 31, v134
	v_add_u32_e32 v136, v178, v140
	v_lshl_add_u64 v[130:131], s[2:3], 0, v[154:155]
	v_lshlrev_b64 v[134:135], 15, v[134:135]
	v_ashrrev_i32_e32 v137, 31, v136
	v_lshl_add_u64 v[132:133], s[10:11], 0, v[154:155]
	v_lshl_add_u64 v[134:135], v[130:131], 0, v[134:135]
	v_lshlrev_b64 v[166:167], 15, v[136:137]
	v_lshl_add_u64 v[136:137], v[132:133], 0, v[166:167]
	v_lshl_add_u64 v[158:159], v[134:135], 0, 0
	global_load_dwordx4 v[182:185], v[134:135], off
	v_lshl_add_u64 v[160:161], v[136:137], 0, 0
	global_load_dwordx4 v[186:189], v[136:137], off
	s_mov_b32 s98, 0x11000
	s_mov_b32 s99, 0x0
	v_lshl_add_u64 v[162:163], v[158:159], 0, s[98:99]
	global_load_dwordx4 v[150:153], v[162:163], off offset:-4096
	s_mov_b32 s98, 0x11000
	s_mov_b32 s99, 0x0
	v_lshl_add_u64 v[164:165], v[160:161], 0, s[98:99]
	global_load_dwordx4 v[146:149], v[164:165], off offset:-4096
	s_mov_b32 s98, 0x1000
	s_mov_b32 s99, 0x0
	v_lshl_add_u64 v[198:199], v[158:159], 0, s[98:99]
	global_load_dwordx4 v[142:145], v[198:199], off offset:-2048
	s_mov_b32 s98, 0x1000
	s_mov_b32 s99, 0x0
	v_lshl_add_u64 v[200:201], v[160:161], 0, s[98:99]
	global_load_dwordx4 v[138:141], v[200:201], off offset:-2048
	global_load_dwordx4 v[134:137], v[162:163], off offset:-2048
	s_nop 0
	global_load_dwordx4 v[130:133], v[164:165], off offset:-2048
	global_load_dwordx4 v[212:215], v[198:199], off
	global_load_dwordx4 v[216:219], v[200:201], off
	global_load_dwordx4 v[220:223], v[162:163], off
	global_load_dwordx4 v[224:227], v[164:165], off
	global_load_dwordx4 v[228:231], v[198:199], off offset:2048
	global_load_dwordx4 v[232:235], v[200:201], off offset:2048
	global_load_dwordx4 v[236:239], v[162:163], off offset:2048
	global_load_dwordx4 v[240:243], v[164:165], off offset:2048
	s_cmpk_lt_i32 s69, 0x80
	s_cselect_b64 s[40:41], -1, 0
	s_xor_b64 s[42:43], s[36:37], -1
	v_lshl_add_u64 v[166:167], s[10:11], 0, v[166:167]
	s_and_b64 s[40:41], s[42:43], s[40:41]
	v_lshl_add_u64 v[166:167], v[166:167], 0, v[154:155]
	s_mov_b64 s[6:7], -1
	s_and_b64 vcc, exec, s[40:41]
	s_waitcnt vmcnt(15)
	v_lshlrev_b32_e32 v190, 16, v182
	v_and_b32_e32 v191, 0xffff0000, v182
	s_waitcnt vmcnt(14)
	v_lshlrev_b32_e32 v192, 16, v186
	v_and_b32_e32 v193, 0xffff0000, v186
	v_lshlrev_b32_e32 v182, 16, v183
	v_and_b32_e32 v183, 0xffff0000, v183
	v_lshlrev_b32_e32 v186, 16, v187
	v_and_b32_e32 v187, 0xffff0000, v187
	v_pk_fma_f32 v[128:129], v[128:129], v[182:183], v[186:187]
	v_lshlrev_b32_e32 v182, 16, v184
	v_and_b32_e32 v183, 0xffff0000, v184
	v_lshlrev_b32_e32 v186, 16, v188
	v_and_b32_e32 v187, 0xffff0000, v188
	v_pk_fma_f32 v[182:183], v[122:123], v[182:183], v[186:187]
	v_lshlrev_b32_e32 v122, 16, v185
	v_and_b32_e32 v123, 0xffff0000, v185
	v_lshlrev_b32_e32 v184, 16, v189
	v_and_b32_e32 v185, 0xffff0000, v189
	v_pk_fma_f32 v[126:127], v[126:127], v[190:191], v[192:193]
	v_pk_fma_f32 v[184:185], v[124:125], v[122:123], v[184:185]
	v_cvt_pk_bf16_f32 v122, v126, v127
	v_cvt_pk_bf16_f32 v123, v128, v129
	v_cvt_pk_bf16_f32 v124, v182, v183
	v_cvt_pk_bf16_f32 v125, v184, v185
	s_cbranch_vccz .LBB0_1380
	global_store_dwordx4 v[200:201], v[122:125], off offset:-4096
	s_mov_b64 s[6:7], 0

.LBB0_1382:
	s_waitcnt vmcnt(13)
	v_lshlrev_b32_e32 v124, 16, v150
	v_and_b32_e32 v125, 0xffff0000, v150
	s_waitcnt vmcnt(12)
	v_lshlrev_b32_e32 v126, 16, v146
	v_and_b32_e32 v127, 0xffff0000, v146
	v_pk_fma_f32 v[118:119], v[118:119], v[124:125], v[126:127]
	v_lshlrev_b32_e32 v124, 16, v151
	v_and_b32_e32 v125, 0xffff0000, v151
	v_lshlrev_b32_e32 v126, 16, v147
	v_and_b32_e32 v127, 0xffff0000, v147
	v_pk_fma_f32 v[120:121], v[120:121], v[124:125], v[126:127]
	v_lshlrev_b32_e32 v124, 16, v152
	v_and_b32_e32 v125, 0xffff0000, v152
	v_lshlrev_b32_e32 v126, 16, v148
	v_and_b32_e32 v127, 0xffff0000, v148
	v_pk_fma_f32 v[124:125], v[114:115], v[124:125], v[126:127]
	v_lshlrev_b32_e32 v114, 16, v153
	v_and_b32_e32 v115, 0xffff0000, v153
	v_lshlrev_b32_e32 v126, 16, v149
	v_and_b32_e32 v127, 0xffff0000, v149
	s_nop 0
	v_pk_fma_f32 v[126:127], v[116:117], v[114:115], v[126:127]
	v_cvt_pk_bf16_f32 v114, v118, v119
	v_cndmask_b32_e64 v118, 0, 1, s[40:41]
	v_cvt_pk_bf16_f32 v115, v120, v121
	v_cvt_pk_bf16_f32 v116, v124, v125
	v_cvt_pk_bf16_f32 v117, v126, v127
	v_cmp_ne_u32_e64 s[6:7], 1, v118
	s_andn2_b64 vcc, exec, s[40:41]
	s_mov_b64 s[40:41], -1
	s_cbranch_vccnz .LBB0_1384
	s_mov_b64 s[40:41], 0
	global_store_dwordx4 v[164:165], v[114:117], off offset:-4096

.LBB0_1386:
	s_waitcnt vmcnt(11)
	v_lshlrev_b32_e32 v116, 16, v142
	v_and_b32_e32 v117, 0xffff0000, v142
	s_waitcnt vmcnt(10)
	v_lshlrev_b32_e32 v118, 16, v138
	v_and_b32_e32 v119, 0xffff0000, v138
	v_pk_fma_f32 v[110:111], v[110:111], v[116:117], v[118:119]
	v_lshlrev_b32_e32 v116, 16, v143
	v_and_b32_e32 v117, 0xffff0000, v143
	v_lshlrev_b32_e32 v118, 16, v139
	v_and_b32_e32 v119, 0xffff0000, v139
	v_pk_fma_f32 v[112:113], v[112:113], v[116:117], v[118:119]
	v_lshlrev_b32_e32 v116, 16, v144
	v_and_b32_e32 v117, 0xffff0000, v144
	v_lshlrev_b32_e32 v118, 16, v140
	v_and_b32_e32 v119, 0xffff0000, v140
	v_pk_fma_f32 v[116:117], v[106:107], v[116:117], v[118:119]
	v_lshlrev_b32_e32 v106, 16, v145
	v_and_b32_e32 v107, 0xffff0000, v145
	v_lshlrev_b32_e32 v118, 16, v141
	v_and_b32_e32 v119, 0xffff0000, v141
	v_pk_fma_f32 v[118:119], v[108:109], v[106:107], v[118:119]
	v_cvt_pk_bf16_f32 v106, v110, v111
	v_cvt_pk_bf16_f32 v107, v112, v113
	v_cvt_pk_bf16_f32 v108, v116, v117
	v_cvt_pk_bf16_f32 v109, v118, v119
	s_and_b64 vcc, exec, s[6:7]
	s_mov_b64 s[40:41], -1
	s_cbranch_vccnz .LBB0_1388
	s_mov_b64 s[40:41], 0
	global_store_dwordx4 v[200:201], v[106:109], off offset:-2048

.LBB0_1390:
	s_waitcnt vmcnt(9)
	v_lshlrev_b32_e32 v108, 16, v134
	v_and_b32_e32 v109, 0xffff0000, v134
	s_waitcnt vmcnt(8)
	v_lshlrev_b32_e32 v110, 16, v130
	v_and_b32_e32 v111, 0xffff0000, v130
	v_pk_fma_f32 v[102:103], v[102:103], v[108:109], v[110:111]
	v_lshlrev_b32_e32 v108, 16, v135
	v_and_b32_e32 v109, 0xffff0000, v135
	v_lshlrev_b32_e32 v110, 16, v131
	v_and_b32_e32 v111, 0xffff0000, v131
	v_pk_fma_f32 v[104:105], v[104:105], v[108:109], v[110:111]
	v_lshlrev_b32_e32 v108, 16, v136
	v_and_b32_e32 v109, 0xffff0000, v136
	v_lshlrev_b32_e32 v110, 16, v132
	v_and_b32_e32 v111, 0xffff0000, v132
	v_pk_fma_f32 v[108:109], v[98:99], v[108:109], v[110:111]
	v_lshlrev_b32_e32 v98, 16, v137
	v_and_b32_e32 v99, 0xffff0000, v137
	v_lshlrev_b32_e32 v110, 16, v133
	v_and_b32_e32 v111, 0xffff0000, v133
	v_pk_fma_f32 v[110:111], v[100:101], v[98:99], v[110:111]
	v_cvt_pk_bf16_f32 v98, v102, v103
	v_cvt_pk_bf16_f32 v99, v104, v105
	v_cvt_pk_bf16_f32 v100, v108, v109
	v_cvt_pk_bf16_f32 v101, v110, v111
	s_and_b64 vcc, exec, s[6:7]
	s_mov_b64 s[40:41], -1
	s_cbranch_vccnz .LBB0_1392
	s_mov_b64 s[40:41], 0
	global_store_dwordx4 v[164:165], v[98:101], off offset:-2048

.LBB0_1394:
	v_add_u32_e32 v100, 32, v177
	s_nop 0
	v_lshrrev_b32_e32 v99, 3, v100
	v_lshlrev_b32_e32 v101, 6, v100
	v_lshlrev_b32_e32 v102, 2, v100
	v_lshlrev_b32_e32 v98, 7, v100
	v_and_or_b32 v99, v99, 14, v176
	v_and_b32_e32 v101, 0x3c0, v101
	v_and_b32_e32 v102, 32, v102
	v_ashrrev_i32_e32 v100, 4, v100
	v_and_b32_e32 v98, 0x4000, v98
	v_lshlrev_b32_e32 v99, 10, v99
	v_bitop3_b32 v101, v101, v102, v175 bitop3:0x36
	v_and_b32_e32 v107, -16, v100
	v_or3_b32 v154, v99, v98, v101
	v_add_u32_e32 v104, v107, v178
	v_ashrrev_i32_e32 v105, 31, v104
	v_lshlrev_b64 v[130:131], 15, v[104:105]
	s_waitcnt vmcnt(4)
	v_mov_b32_e32 v132, v212
	v_mov_b32_e32 v133, v213
	v_mov_b32_e32 v134, v214
	v_mov_b32_e32 v135, v215
	v_mov_b32_e32 v136, v216
	v_mov_b32_e32 v137, v217
	v_mov_b32_e32 v138, v218
	v_mov_b32_e32 v139, v219
	v_mov_b32_e32 v118, v220
	v_mov_b32_e32 v119, v221
	v_mov_b32_e32 v120, v222
	v_mov_b32_e32 v121, v223
	v_mov_b32_e32 v114, v224
	v_mov_b32_e32 v115, v225
	v_mov_b32_e32 v116, v226
	v_mov_b32_e32 v117, v227
	v_mov_b32_e32 v110, v228
	v_mov_b32_e32 v111, v229
	v_mov_b32_e32 v112, v230
	v_mov_b32_e32 v113, v231
	v_mov_b32_e32 v106, v232
	v_mov_b32_e32 v107, v233
	v_mov_b32_e32 v108, v234
	v_mov_b32_e32 v109, v235
	v_mov_b32_e32 v102, v236
	v_mov_b32_e32 v103, v237
	v_mov_b32_e32 v104, v238
	v_mov_b32_e32 v105, v239
	s_nop 0
	v_mov_b32_e32 v98, v240
	v_mov_b32_e32 v99, v241
	v_mov_b32_e32 v100, v242
	v_mov_b32_e32 v101, v243
	s_mov_b32 s98, 0x5000
	s_mov_b32 s99, 0x0
	v_lshl_add_u64 v[204:205], v[158:159], 0, s[98:99]
	v_lshl_add_u64 v[206:207], v[160:161], 0, s[98:99]
	s_mov_b32 s98, 0x15000
	s_mov_b32 s99, 0x0
	v_lshl_add_u64 v[208:209], v[158:159], 0, s[98:99]
	v_lshl_add_u64 v[250:251], v[160:161], 0, s[98:99]
	global_load_dwordx4 v[212:215], v[204:205], off offset:-4096
	global_load_dwordx4 v[216:219], v[206:207], off offset:-4096
	global_load_dwordx4 v[220:223], v[208:209], off offset:-4096
	global_load_dwordx4 v[224:227], v[250:251], off offset:-4096
	global_load_dwordx4 v[228:231], v[204:205], off offset:-2048
	global_load_dwordx4 v[232:235], v[206:207], off offset:-2048
	global_load_dwordx4 v[236:239], v[208:209], off offset:-2048
	global_load_dwordx4 v[240:243], v[250:251], off offset:-2048
	v_lshl_add_u64 v[130:131], s[10:11], 0, v[130:131]
	v_lshl_add_u64 v[130:131], v[130:131], 0, v[154:155]
	s_and_b64 vcc, exec, s[6:7]
	s_mov_b64 s[40:41], -1
	v_lshlrev_b32_e32 v140, 16, v132
	v_and_b32_e32 v141, 0xffff0000, v132
	v_lshlrev_b32_e32 v142, 16, v136
	v_and_b32_e32 v143, 0xffff0000, v136
	v_lshlrev_b32_e32 v132, 16, v133
	v_and_b32_e32 v133, 0xffff0000, v133
	v_lshlrev_b32_e32 v136, 16, v137
	v_and_b32_e32 v137, 0xffff0000, v137
	v_pk_fma_f32 v[96:97], v[96:97], v[132:133], v[136:137]
	v_lshlrev_b32_e32 v132, 16, v134
	v_and_b32_e32 v133, 0xffff0000, v134
	v_lshlrev_b32_e32 v136, 16, v138
	v_and_b32_e32 v137, 0xffff0000, v138
	v_pk_fma_f32 v[132:133], v[90:91], v[132:133], v[136:137]
	v_lshlrev_b32_e32 v90, 16, v135
	v_and_b32_e32 v91, 0xffff0000, v135
	v_lshlrev_b32_e32 v134, 16, v139
	v_and_b32_e32 v135, 0xffff0000, v139
	v_pk_fma_f32 v[94:95], v[94:95], v[140:141], v[142:143]
	v_pk_fma_f32 v[134:135], v[92:93], v[90:91], v[134:135]
	v_cvt_pk_bf16_f32 v90, v94, v95
	v_cvt_pk_bf16_f32 v91, v96, v97
	v_cvt_pk_bf16_f32 v92, v132, v133
	v_cvt_pk_bf16_f32 v93, v134, v135
	s_cbranch_vccnz .LBB0_1396
	s_mov_b64 s[40:41], 0
	global_store_dwordx4 v[200:201], v[90:93], off

.LBB0_1398:
	v_lshlrev_b32_e32 v92, 16, v118
	v_and_b32_e32 v93, 0xffff0000, v118
	v_lshlrev_b32_e32 v94, 16, v114
	v_and_b32_e32 v95, 0xffff0000, v114
	v_pk_fma_f32 v[86:87], v[86:87], v[92:93], v[94:95]
	v_lshlrev_b32_e32 v92, 16, v119
	v_and_b32_e32 v93, 0xffff0000, v119
	v_lshlrev_b32_e32 v94, 16, v115
	v_and_b32_e32 v95, 0xffff0000, v115
	v_pk_fma_f32 v[88:89], v[88:89], v[92:93], v[94:95]
	v_lshlrev_b32_e32 v92, 16, v120
	v_and_b32_e32 v93, 0xffff0000, v120
	v_lshlrev_b32_e32 v94, 16, v116
	v_and_b32_e32 v95, 0xffff0000, v116
	v_pk_fma_f32 v[92:93], v[82:83], v[92:93], v[94:95]
	v_lshlrev_b32_e32 v82, 16, v121
	v_and_b32_e32 v83, 0xffff0000, v121
	v_lshlrev_b32_e32 v94, 16, v117
	v_and_b32_e32 v95, 0xffff0000, v117
	v_pk_fma_f32 v[94:95], v[84:85], v[82:83], v[94:95]
	v_cvt_pk_bf16_f32 v82, v86, v87
	v_cvt_pk_bf16_f32 v83, v88, v89
	v_cvt_pk_bf16_f32 v84, v92, v93
	v_cvt_pk_bf16_f32 v85, v94, v95
	s_and_b64 vcc, exec, s[6:7]
	s_mov_b64 s[40:41], -1
	s_cbranch_vccnz .LBB0_1400
	s_mov_b64 s[40:41], 0
	global_store_dwordx4 v[164:165], v[82:85], off

.LBB0_1402:
	v_lshlrev_b32_e32 v84, 16, v110
	v_and_b32_e32 v85, 0xffff0000, v110
	v_lshlrev_b32_e32 v86, 16, v106
	v_and_b32_e32 v87, 0xffff0000, v106
	v_pk_fma_f32 v[78:79], v[78:79], v[84:85], v[86:87]
	v_lshlrev_b32_e32 v84, 16, v111
	v_and_b32_e32 v85, 0xffff0000, v111
	v_lshlrev_b32_e32 v86, 16, v107
	v_and_b32_e32 v87, 0xffff0000, v107
	v_pk_fma_f32 v[80:81], v[80:81], v[84:85], v[86:87]
	v_lshlrev_b32_e32 v84, 16, v112
	v_and_b32_e32 v85, 0xffff0000, v112
	v_lshlrev_b32_e32 v86, 16, v108
	v_and_b32_e32 v87, 0xffff0000, v108
	v_pk_fma_f32 v[84:85], v[74:75], v[84:85], v[86:87]
	v_lshlrev_b32_e32 v74, 16, v113
	v_and_b32_e32 v75, 0xffff0000, v113
	v_lshlrev_b32_e32 v86, 16, v109
	v_and_b32_e32 v87, 0xffff0000, v109
	v_pk_fma_f32 v[86:87], v[76:77], v[74:75], v[86:87]
	v_cvt_pk_bf16_f32 v74, v78, v79
	v_cvt_pk_bf16_f32 v75, v80, v81
	v_cvt_pk_bf16_f32 v76, v84, v85
	v_cvt_pk_bf16_f32 v77, v86, v87
	s_and_b64 vcc, exec, s[6:7]
	s_mov_b64 s[40:41], -1
	s_cbranch_vccnz .LBB0_1404
	s_mov_b64 s[40:41], 0
	global_store_dwordx4 v[200:201], v[74:77], off offset:2048

.LBB0_1406:
	v_lshlrev_b32_e32 v76, 16, v102
	v_and_b32_e32 v77, 0xffff0000, v102
	v_lshlrev_b32_e32 v78, 16, v98
	v_and_b32_e32 v79, 0xffff0000, v98
	v_pk_fma_f32 v[70:71], v[70:71], v[76:77], v[78:79]
	v_lshlrev_b32_e32 v76, 16, v103
	v_and_b32_e32 v77, 0xffff0000, v103
	v_lshlrev_b32_e32 v78, 16, v99
	v_and_b32_e32 v79, 0xffff0000, v99
	v_pk_fma_f32 v[72:73], v[72:73], v[76:77], v[78:79]
	v_lshlrev_b32_e32 v76, 16, v104
	v_and_b32_e32 v77, 0xffff0000, v104
	v_lshlrev_b32_e32 v78, 16, v100
	v_and_b32_e32 v79, 0xffff0000, v100
	v_pk_fma_f32 v[76:77], v[66:67], v[76:77], v[78:79]
	v_lshlrev_b32_e32 v66, 16, v105
	v_and_b32_e32 v67, 0xffff0000, v105
	v_lshlrev_b32_e32 v78, 16, v101
	v_and_b32_e32 v79, 0xffff0000, v101
	v_pk_fma_f32 v[78:79], v[68:69], v[66:67], v[78:79]
	v_cvt_pk_bf16_f32 v66, v70, v71
	v_cvt_pk_bf16_f32 v67, v72, v73
	v_cvt_pk_bf16_f32 v68, v76, v77
	v_cvt_pk_bf16_f32 v69, v78, v79
	s_and_b64 vcc, exec, s[6:7]
	s_mov_b64 s[40:41], -1
	s_cbranch_vccnz .LBB0_1408
	s_mov_b64 s[40:41], 0
	global_store_dwordx4 v[164:165], v[66:69], off offset:2048

.LBB0_1410:
	s_nop 0
	s_nop 0
	s_nop 0
	s_nop 0
	s_mov_b32 s98, 0x5000
	s_mov_b32 s99, 0x0
	v_lshl_add_u64 v[162:163], v[158:159], 0, s[98:99]
	s_waitcnt vmcnt(4)
	v_mov_b32_e32 v100, v212
	v_mov_b32_e32 v101, v213
	v_mov_b32_e32 v102, v214
	v_mov_b32_e32 v103, v215
	s_mov_b32 s98, 0x5000
	s_mov_b32 s99, 0x0
	v_lshl_add_u64 v[164:165], v[160:161], 0, s[98:99]
	v_mov_b32_e32 v104, v216
	v_mov_b32_e32 v105, v217
	v_mov_b32_e32 v106, v218
	v_mov_b32_e32 v107, v219
	s_mov_b32 s98, 0x15000
	s_mov_b32 s99, 0x0
	v_lshl_add_u64 v[198:199], v[158:159], 0, s[98:99]
	v_mov_b32_e32 v86, v220
	v_mov_b32_e32 v87, v221
	v_mov_b32_e32 v88, v222
	v_mov_b32_e32 v89, v223
	s_mov_b32 s98, 0x15000
	s_mov_b32 s99, 0x0
	v_lshl_add_u64 v[158:159], v[160:161], 0, s[98:99]
	v_mov_b32_e32 v82, v224
	v_mov_b32_e32 v83, v225
	v_mov_b32_e32 v84, v226
	v_mov_b32_e32 v85, v227
	v_mov_b32_e32 v78, v228
	v_mov_b32_e32 v79, v229
	v_mov_b32_e32 v80, v230
	v_mov_b32_e32 v81, v231
	v_mov_b32_e32 v74, v232
	v_mov_b32_e32 v75, v233
	v_mov_b32_e32 v76, v234
	v_mov_b32_e32 v77, v235
	v_mov_b32_e32 v70, v236
	v_mov_b32_e32 v71, v237
	v_mov_b32_e32 v72, v238
	v_mov_b32_e32 v73, v239
	s_nop 0
	v_mov_b32_e32 v66, v240
	v_mov_b32_e32 v67, v241
	v_mov_b32_e32 v68, v242
	v_mov_b32_e32 v69, v243
	global_load_dwordx4 v[212:215], v[204:205], off
	global_load_dwordx4 v[216:219], v[206:207], off
	global_load_dwordx4 v[220:223], v[208:209], off
	global_load_dwordx4 v[224:227], v[250:251], off
	global_load_dwordx4 v[228:231], v[204:205], off offset:2048
	global_load_dwordx4 v[232:235], v[206:207], off offset:2048
	global_load_dwordx4 v[236:239], v[208:209], off offset:2048
	global_load_dwordx4 v[240:243], v[250:251], off offset:2048
	s_and_b64 vcc, exec, s[6:7]
	s_mov_b64 s[40:41], -1
	v_lshlrev_b32_e32 v108, 16, v100
	v_and_b32_e32 v109, 0xffff0000, v100
	v_lshlrev_b32_e32 v110, 16, v104
	v_and_b32_e32 v111, 0xffff0000, v104
	v_lshlrev_b32_e32 v100, 16, v101
	v_and_b32_e32 v101, 0xffff0000, v101
	v_lshlrev_b32_e32 v104, 16, v105
	v_and_b32_e32 v105, 0xffff0000, v105
	v_lshlrev_b32_e32 v112, 16, v102
	v_and_b32_e32 v113, 0xffff0000, v102
	v_pk_fma_f32 v[64:65], v[64:65], v[100:101], v[104:105]
	v_lshlrev_b32_e32 v100, 16, v106
	v_and_b32_e32 v101, 0xffff0000, v106
	v_pk_fma_f32 v[100:101], v[58:59], v[112:113], v[100:101]
	v_lshlrev_b32_e32 v58, 16, v103
	v_and_b32_e32 v59, 0xffff0000, v103
	v_lshlrev_b32_e32 v102, 16, v107
	v_and_b32_e32 v103, 0xffff0000, v107
	v_pk_fma_f32 v[62:63], v[62:63], v[108:109], v[110:111]
	v_pk_fma_f32 v[102:103], v[60:61], v[58:59], v[102:103]
	v_cvt_pk_bf16_f32 v58, v62, v63
	v_cvt_pk_bf16_f32 v59, v64, v65
	v_cvt_pk_bf16_f32 v60, v100, v101
	v_cvt_pk_bf16_f32 v61, v102, v103
	s_cbranch_vccnz .LBB0_1412
	s_mov_b64 s[40:41], 0
	global_store_dwordx4 v[164:165], v[58:61], off offset:-4096

.LBB0_1414:
	v_lshlrev_b32_e32 v60, 16, v86
	v_and_b32_e32 v61, 0xffff0000, v86
	v_lshlrev_b32_e32 v62, 16, v82
	v_and_b32_e32 v63, 0xffff0000, v82
	v_pk_fma_f32 v[54:55], v[54:55], v[60:61], v[62:63]
	v_lshlrev_b32_e32 v60, 16, v87
	v_and_b32_e32 v61, 0xffff0000, v87
	v_lshlrev_b32_e32 v62, 16, v83
	v_and_b32_e32 v63, 0xffff0000, v83
	v_pk_fma_f32 v[56:57], v[56:57], v[60:61], v[62:63]
	v_lshlrev_b32_e32 v60, 16, v88
	v_and_b32_e32 v61, 0xffff0000, v88
	v_lshlrev_b32_e32 v62, 16, v84
	v_and_b32_e32 v63, 0xffff0000, v84
	v_pk_fma_f32 v[60:61], v[50:51], v[60:61], v[62:63]
	v_lshlrev_b32_e32 v50, 16, v89
	v_and_b32_e32 v51, 0xffff0000, v89
	v_lshlrev_b32_e32 v62, 16, v85
	v_and_b32_e32 v63, 0xffff0000, v85
	v_pk_fma_f32 v[62:63], v[52:53], v[50:51], v[62:63]
	v_cvt_pk_bf16_f32 v50, v54, v55
	v_cvt_pk_bf16_f32 v51, v56, v57
	v_cvt_pk_bf16_f32 v52, v60, v61
	v_cvt_pk_bf16_f32 v53, v62, v63
	s_and_b64 vcc, exec, s[6:7]
	s_mov_b64 s[40:41], -1
	s_cbranch_vccnz .LBB0_1416
	s_mov_b64 s[40:41], 0
	global_store_dwordx4 v[158:159], v[50:53], off offset:-4096

.LBB0_1418:
	v_lshlrev_b32_e32 v52, 16, v78
	v_and_b32_e32 v53, 0xffff0000, v78
	v_lshlrev_b32_e32 v54, 16, v74
	v_and_b32_e32 v55, 0xffff0000, v74
	v_pk_fma_f32 v[46:47], v[46:47], v[52:53], v[54:55]
	v_lshlrev_b32_e32 v52, 16, v79
	v_and_b32_e32 v53, 0xffff0000, v79
	v_lshlrev_b32_e32 v54, 16, v75
	v_and_b32_e32 v55, 0xffff0000, v75
	v_pk_fma_f32 v[48:49], v[48:49], v[52:53], v[54:55]
	v_lshlrev_b32_e32 v52, 16, v80
	v_and_b32_e32 v53, 0xffff0000, v80
	v_lshlrev_b32_e32 v54, 16, v76
	v_and_b32_e32 v55, 0xffff0000, v76
	v_pk_fma_f32 v[52:53], v[42:43], v[52:53], v[54:55]
	v_lshlrev_b32_e32 v42, 16, v81
	v_and_b32_e32 v43, 0xffff0000, v81
	v_lshlrev_b32_e32 v54, 16, v77
	v_and_b32_e32 v55, 0xffff0000, v77
	v_pk_fma_f32 v[54:55], v[44:45], v[42:43], v[54:55]
	v_cvt_pk_bf16_f32 v42, v46, v47
	v_cvt_pk_bf16_f32 v43, v48, v49
	v_cvt_pk_bf16_f32 v44, v52, v53
	v_cvt_pk_bf16_f32 v45, v54, v55
	s_and_b64 vcc, exec, s[6:7]
	s_mov_b64 s[40:41], -1
	s_cbranch_vccnz .LBB0_1420
	s_mov_b64 s[40:41], 0
	global_store_dwordx4 v[164:165], v[42:45], off offset:-2048

.LBB0_1422:
	v_lshlrev_b32_e32 v44, 16, v70
	v_and_b32_e32 v45, 0xffff0000, v70
	v_lshlrev_b32_e32 v46, 16, v66
	v_and_b32_e32 v47, 0xffff0000, v66
	v_pk_fma_f32 v[38:39], v[38:39], v[44:45], v[46:47]
	v_lshlrev_b32_e32 v44, 16, v71
	v_and_b32_e32 v45, 0xffff0000, v71
	v_lshlrev_b32_e32 v46, 16, v67
	v_and_b32_e32 v47, 0xffff0000, v67
	v_pk_fma_f32 v[40:41], v[40:41], v[44:45], v[46:47]
	v_lshlrev_b32_e32 v44, 16, v72
	v_and_b32_e32 v45, 0xffff0000, v72
	v_lshlrev_b32_e32 v46, 16, v68
	v_and_b32_e32 v47, 0xffff0000, v68
	v_pk_fma_f32 v[44:45], v[34:35], v[44:45], v[46:47]
	v_lshlrev_b32_e32 v34, 16, v73
	v_and_b32_e32 v35, 0xffff0000, v73
	v_lshlrev_b32_e32 v46, 16, v69
	v_and_b32_e32 v47, 0xffff0000, v69
	v_pk_fma_f32 v[46:47], v[36:37], v[34:35], v[46:47]
	v_cvt_pk_bf16_f32 v34, v38, v39
	v_cvt_pk_bf16_f32 v35, v40, v41
	v_cvt_pk_bf16_f32 v36, v44, v45
	v_cvt_pk_bf16_f32 v37, v46, v47
	s_and_b64 vcc, exec, s[6:7]
	s_mov_b64 s[40:41], -1
	s_cbranch_vccnz .LBB0_1424
	s_mov_b64 s[40:41], 0
	global_store_dwordx4 v[158:159], v[34:37], off offset:-2048

.LBB0_1426:
	v_add_u32_e32 v36, 0xa0, v177
	s_nop 0
	v_lshrrev_b32_e32 v35, 3, v36
	v_lshlrev_b32_e32 v37, 6, v36
	v_lshlrev_b32_e32 v38, 2, v36
	v_lshlrev_b32_e32 v34, 7, v36
	v_and_or_b32 v35, v35, 14, v176
	v_and_b32_e32 v37, 0x3c0, v37
	v_and_b32_e32 v38, 32, v38
	v_and_b32_e32 v34, 0x4000, v34
	v_lshlrev_b32_e32 v35, 10, v35
	v_bitop3_b32 v37, v37, v38, v175 bitop3:0x36
	v_or3_b32 v154, v35, v34, v37
	s_waitcnt vmcnt(4)
	v_mov_b32_e32 v68, v212
	v_mov_b32_e32 v69, v213
	v_mov_b32_e32 v70, v214
	v_mov_b32_e32 v71, v215
	v_mov_b32_e32 v72, v216
	v_mov_b32_e32 v73, v217
	v_mov_b32_e32 v74, v218
	v_mov_b32_e32 v75, v219
	v_mov_b32_e32 v54, v220
	v_mov_b32_e32 v55, v221
	v_mov_b32_e32 v56, v222
	v_mov_b32_e32 v57, v223
	v_mov_b32_e32 v50, v224
	v_mov_b32_e32 v51, v225
	v_mov_b32_e32 v52, v226
	v_mov_b32_e32 v53, v227
	v_mov_b32_e32 v46, v228
	v_mov_b32_e32 v47, v229
	v_mov_b32_e32 v48, v230
	v_mov_b32_e32 v49, v231
	v_mov_b32_e32 v42, v232
	v_mov_b32_e32 v43, v233
	v_mov_b32_e32 v44, v234
	v_mov_b32_e32 v45, v235
	v_mov_b32_e32 v38, v236
	v_mov_b32_e32 v39, v237
	v_mov_b32_e32 v40, v238
	v_mov_b32_e32 v41, v239
	s_nop 0
	v_mov_b32_e32 v34, v240
	v_mov_b32_e32 v35, v241
	v_mov_b32_e32 v36, v242
	v_mov_b32_e32 v37, v243
	s_and_b64 vcc, exec, s[6:7]
	s_mov_b64 s[40:41], -1
	v_lshlrev_b32_e32 v76, 16, v68
	v_and_b32_e32 v77, 0xffff0000, v68
	v_lshlrev_b32_e32 v78, 16, v72
	v_and_b32_e32 v79, 0xffff0000, v72
	v_lshlrev_b32_e32 v68, 16, v69
	v_and_b32_e32 v69, 0xffff0000, v69
	v_lshlrev_b32_e32 v72, 16, v73
	v_and_b32_e32 v73, 0xffff0000, v73
	v_pk_fma_f32 v[32:33], v[32:33], v[68:69], v[72:73]
	v_lshlrev_b32_e32 v68, 16, v70
	v_and_b32_e32 v69, 0xffff0000, v70
	v_lshlrev_b32_e32 v72, 16, v74
	v_and_b32_e32 v73, 0xffff0000, v74
	v_pk_fma_f32 v[68:69], v[26:27], v[68:69], v[72:73]
	v_lshlrev_b32_e32 v26, 16, v71
	v_and_b32_e32 v27, 0xffff0000, v71
	v_lshlrev_b32_e32 v70, 16, v75
	v_and_b32_e32 v71, 0xffff0000, v75
	v_pk_fma_f32 v[30:31], v[30:31], v[76:77], v[78:79]
	v_pk_fma_f32 v[70:71], v[28:29], v[26:27], v[70:71]
	v_cvt_pk_bf16_f32 v26, v30, v31
	v_cvt_pk_bf16_f32 v27, v32, v33
	v_cvt_pk_bf16_f32 v28, v68, v69
	v_cvt_pk_bf16_f32 v29, v70, v71
	s_cbranch_vccnz .LBB0_1428
	s_mov_b64 s[40:41], 0
	global_store_dwordx4 v[164:165], v[26:29], off

.LBB0_1430:
	v_lshlrev_b32_e32 v28, 16, v54
	v_and_b32_e32 v29, 0xffff0000, v54
	v_lshlrev_b32_e32 v30, 16, v50
	v_and_b32_e32 v31, 0xffff0000, v50
	v_pk_fma_f32 v[22:23], v[22:23], v[28:29], v[30:31]
	v_lshlrev_b32_e32 v28, 16, v55
	v_and_b32_e32 v29, 0xffff0000, v55
	v_lshlrev_b32_e32 v30, 16, v51
	v_and_b32_e32 v31, 0xffff0000, v51
	v_pk_fma_f32 v[24:25], v[24:25], v[28:29], v[30:31]
	v_lshlrev_b32_e32 v28, 16, v56
	v_and_b32_e32 v29, 0xffff0000, v56
	v_lshlrev_b32_e32 v30, 16, v52
	v_and_b32_e32 v31, 0xffff0000, v52
	v_pk_fma_f32 v[28:29], v[18:19], v[28:29], v[30:31]
	v_lshlrev_b32_e32 v18, 16, v57
	v_and_b32_e32 v19, 0xffff0000, v57
	v_lshlrev_b32_e32 v30, 16, v53
	v_and_b32_e32 v31, 0xffff0000, v53
	v_pk_fma_f32 v[30:31], v[20:21], v[18:19], v[30:31]
	v_cvt_pk_bf16_f32 v18, v22, v23
	v_cvt_pk_bf16_f32 v19, v24, v25
	v_cvt_pk_bf16_f32 v20, v28, v29
	v_cvt_pk_bf16_f32 v21, v30, v31
	s_and_b64 vcc, exec, s[6:7]
	s_mov_b64 s[40:41], -1
	s_cbranch_vccnz .LBB0_1432
	s_mov_b64 s[40:41], 0
	global_store_dwordx4 v[158:159], v[18:21], off

.LBB0_1434:
	v_lshlrev_b32_e32 v20, 16, v46
	v_and_b32_e32 v21, 0xffff0000, v46
	v_lshlrev_b32_e32 v22, 16, v42
	v_and_b32_e32 v23, 0xffff0000, v42
	v_pk_fma_f32 v[14:15], v[14:15], v[20:21], v[22:23]
	v_lshlrev_b32_e32 v20, 16, v47
	v_and_b32_e32 v21, 0xffff0000, v47
	v_lshlrev_b32_e32 v22, 16, v43
	v_and_b32_e32 v23, 0xffff0000, v43
	v_pk_fma_f32 v[16:17], v[16:17], v[20:21], v[22:23]
	v_lshlrev_b32_e32 v20, 16, v48
	v_and_b32_e32 v21, 0xffff0000, v48
	v_lshlrev_b32_e32 v22, 16, v44
	v_and_b32_e32 v23, 0xffff0000, v44
	v_pk_fma_f32 v[20:21], v[10:11], v[20:21], v[22:23]
	v_lshlrev_b32_e32 v10, 16, v49
	v_and_b32_e32 v11, 0xffff0000, v49
	v_lshlrev_b32_e32 v22, 16, v45
	v_and_b32_e32 v23, 0xffff0000, v45
	v_pk_fma_f32 v[22:23], v[12:13], v[10:11], v[22:23]
	v_cvt_pk_bf16_f32 v10, v14, v15
	v_cvt_pk_bf16_f32 v11, v16, v17
	v_cvt_pk_bf16_f32 v12, v20, v21
	v_cvt_pk_bf16_f32 v13, v22, v23
	s_and_b64 vcc, exec, s[6:7]
	s_mov_b64 s[40:41], -1
	s_cbranch_vccnz .LBB0_1436
	s_mov_b64 s[40:41], 0
	global_store_dwordx4 v[164:165], v[10:13], off offset:2048

.LBB0_1438:
	v_lshlrev_b32_e32 v12, 16, v38
	v_and_b32_e32 v13, 0xffff0000, v38
	v_lshlrev_b32_e32 v14, 16, v34
	v_and_b32_e32 v15, 0xffff0000, v34
	v_pk_fma_f32 v[6:7], v[6:7], v[12:13], v[14:15]
	v_lshlrev_b32_e32 v12, 16, v39
	v_and_b32_e32 v13, 0xffff0000, v39
	v_lshlrev_b32_e32 v14, 16, v35
	v_and_b32_e32 v15, 0xffff0000, v35
	v_pk_fma_f32 v[8:9], v[8:9], v[12:13], v[14:15]
	v_lshlrev_b32_e32 v12, 16, v40
	v_and_b32_e32 v13, 0xffff0000, v40
	v_lshlrev_b32_e32 v14, 16, v36
	v_and_b32_e32 v15, 0xffff0000, v36
	v_pk_fma_f32 v[12:13], v[2:3], v[12:13], v[14:15]
	v_lshlrev_b32_e32 v2, 16, v41
	v_and_b32_e32 v3, 0xffff0000, v41
	v_lshlrev_b32_e32 v14, 16, v37
	v_and_b32_e32 v15, 0xffff0000, v37
	v_pk_fma_f32 v[14:15], v[4:5], v[2:3], v[14:15]
	v_cvt_pk_bf16_f32 v2, v6, v7
	v_cvt_pk_bf16_f32 v3, v8, v9
	v_cvt_pk_bf16_f32 v4, v12, v13
	v_cvt_pk_bf16_f32 v5, v14, v15
	s_and_b64 vcc, exec, s[6:7]
	s_mov_b64 s[6:7], -1
	s_cbranch_vccnz .LBB0_1440
	s_mov_b64 s[6:7], 0
	global_store_dwordx4 v[158:159], v[2:5], off offset:2048
